# scan_post and mla_finalize reductions with DPP row ops instead of LDS permutes; attention running-max half exchange with v_permlane32_swap instead of ds_bpermute
# baseline (speedup 1.0000x reference)
; #define MFMA(a, b, c) __builtin_amdgcn_mfma_f32_32x32x16_bf16((a), (b), (c), 0, 0, 0)
; template <int DQK, bool SWA> ...
;     ...
;     float mx = -INFINITY;
; #pragma unroll
;     for (int mt = 0; mt < 2; ++mt)
; #pragma unroll
;       for (int i = 0; i < 16; ++i) mx = fmaxf(mx, s[mt][i]);
;     mx = fmaxf(mx, __shfl_xor(mx, 32));
;     const float mnew = fmaxf(m, mx);
;     const float alpha = __builtin_amdgcn_exp2f(m - mnew);
;     m = mnew;
;     float psum = 0.f;
; #pragma unroll
;     for (int mt = 0; mt < 2; ++mt)
; #pragma unroll
;       for (int i = 0; i < 16; ++i) {
;         const float pv = __builtin_amdgcn_exp2f(s[mt][i] - mnew);
;         s[mt][i] = pv;
;         psum += pv;
;       }
;     lsum = lsum * alpha + psum;
; #pragma unroll
;     for (int a = 0; a < 2; ++a)
; #pragma unroll
;       for (int i = 0; i < 16; ++i) o[a][i] *= alpha;
; #pragma unroll
;     for (int mt = 0; mt < 2; ++mt)
; #pragma unroll
;       for (int sx = 0; sx < 2; ++sx) {
;         uint4 pu;
;         pu.x = pack2(s[mt][8 * sx + 0], s[mt][8 * sx + 1]);
;         pu.y = pack2(s[mt][8 * sx + 2], s[mt][8 * sx + 3]);
;         pu.z = pack2(s[mt][8 * sx + 4], s[mt][8 * sx + 5]);
;         pu.w = pack2(s[mt][8 * sx + 6], s[mt][8 * sx + 7]);
;         const bf16x8 pfv = __builtin_bit_cast(bf16x8, pu);
; #pragma unroll
;         for (int dt = 0; dt < 2; ++dt) {
;           const u16* vp = Vt + buf * 64 * VSTR + (dt * 32 + r) * VSTR + mt * 32 + 16 * sx + 4 * hh;
;           const uint2 v0 = *(const uint2*)(vp);
;           const uint2 v1 = *(const uint2*)(vp + 8);
;           const uint4 vu = make_uint4(v0.x, v0.y, v1.x, v1.y);
;           o[dt] = MFMA(__builtin_bit_cast(bf16x8, vu), pfv, o[dt]);
;         }
;       }
;     if (it + 1 < nt) A_STORES(buf ^ 1);
.LBB0_777:
	s_nop 0
	v_max3_f32 v153, v48, s22, v49
	v_max3_f32 v153, v153, v50, v51
	v_max3_f32 v153, v153, v52, v53
	v_max3_f32 v153, v153, v54, v55
	v_max3_f32 v153, v153, v56, v57
	v_max3_f32 v153, v153, v58, v59
	v_max3_f32 v153, v153, v60, v61
	v_max3_f32 v153, v153, v62, v63
	s_nop 1
	v_max3_f32 v153, v153, v32, v33
	v_max3_f32 v153, v153, v34, v35
	v_max3_f32 v153, v153, v36, v37
	v_max3_f32 v153, v153, v38, v39
	v_max3_f32 v153, v153, v40, v41
	v_max3_f32 v153, v153, v42, v43
	v_max3_f32 v153, v153, v44, v45
	v_max3_f32 v153, v153, v46, v47
	v_mov_b32_e32 v155, v153
	s_nop 1
	v_permlane32_swap_b32 v155, v153
	s_andn2_b64 vcc, exec, s[0:1]
	s_waitcnt lgkmcnt(0)
	v_max3_f32 v153, v154, v153, v155
	v_sub_f32_e32 v155, v48, v153
	v_sub_f32_e32 v156, v49, v153
	v_exp_f32_e32 v49, v155
	v_add_u32_e32 v155, s5, v129
	v_sub_f32_e32 v154, v154, v153
	v_add_u32_e32 v168, 0x4800, v155
	v_exp_f32_e32 v48, v154
	v_exp_f32_e32 v154, v156
	ds_read2_b64 v[156:159], v168 offset1:2
	v_sub_f32_e32 v50, v50, v153
	v_sub_f32_e32 v51, v51, v153
	v_sub_f32_e32 v52, v52, v153
	v_sub_f32_e32 v53, v53, v153
	v_sub_f32_e32 v54, v54, v153
	v_sub_f32_e32 v55, v55, v153
	v_exp_f32_e32 v50, v50
	v_exp_f32_e32 v51, v51
	v_exp_f32_e32 v52, v52
	v_exp_f32_e32 v53, v53
	v_exp_f32_e32 v54, v54
	v_exp_f32_e32 v55, v55
	v_add_u32_e32 v155, 0x5800, v155
	v_pk_mul_f32 v[30:31], v[30:31], v[48:49] op_sel_hi:[1,0]
	v_pk_mul_f32 v[28:29], v[28:29], v[48:49] op_sel_hi:[1,0]
	v_pk_mul_f32 v[26:27], v[26:27], v[48:49] op_sel_hi:[1,0]
	v_pk_mul_f32 v[24:25], v[24:25], v[48:49] op_sel_hi:[1,0]
	v_pk_mul_f32 v[22:23], v[22:23], v[48:49] op_sel_hi:[1,0]
	v_pk_mul_f32 v[20:21], v[20:21], v[48:49] op_sel_hi:[1,0]
	v_pk_mul_f32 v[18:19], v[18:19], v[48:49] op_sel_hi:[1,0]
	v_pk_mul_f32 v[16:17], v[16:17], v[48:49] op_sel_hi:[1,0]
	v_cvt_pk_bf16_f32 v160, v49, v154
	v_cvt_pk_bf16_f32 v161, v50, v51
	v_cvt_pk_bf16_f32 v162, v52, v53
	v_cvt_pk_bf16_f32 v163, v54, v55
	ds_read2_b64 v[164:167], v155 offset0:64 offset1:66
	v_sub_f32_e32 v56, v56, v153
	s_waitcnt lgkmcnt(1)
	v_mfma_f32_32x32x16_bf16 v[16:31], v[156:159], v[160:163], v[16:31]
	ds_read2_b64 v[156:159], v168 offset0:4 offset1:6
	v_sub_f32_e32 v57, v57, v153
	v_sub_f32_e32 v58, v58, v153
	v_sub_f32_e32 v59, v59, v153
	v_sub_f32_e32 v60, v60, v153
	v_sub_f32_e32 v61, v61, v153
	v_sub_f32_e32 v62, v62, v153
	v_sub_f32_e32 v63, v63, v153
	v_exp_f32_e32 v56, v56
	v_exp_f32_e32 v57, v57
	v_exp_f32_e32 v58, v58
	v_exp_f32_e32 v59, v59
	v_exp_f32_e32 v60, v60
	v_exp_f32_e32 v61, v61
	v_exp_f32_e32 v62, v62
	v_exp_f32_e32 v63, v63
	v_pk_mul_f32 v[14:15], v[14:15], v[48:49] op_sel_hi:[1,0]
	v_pk_mul_f32 v[12:13], v[12:13], v[48:49] op_sel_hi:[1,0]
	v_pk_mul_f32 v[10:11], v[10:11], v[48:49] op_sel_hi:[1,0]
	v_pk_mul_f32 v[8:9], v[8:9], v[48:49] op_sel_hi:[1,0]
	v_pk_mul_f32 v[6:7], v[6:7], v[48:49] op_sel_hi:[1,0]
	v_pk_mul_f32 v[4:5], v[4:5], v[48:49] op_sel_hi:[1,0]
	v_pk_mul_f32 v[2:3], v[2:3], v[48:49] op_sel_hi:[1,0]
	v_pk_mul_f32 v[0:1], v[0:1], v[48:49] op_sel_hi:[1,0]
	v_sub_f32_e32 v32, v32, v153
	v_sub_f32_e32 v33, v33, v153
	s_waitcnt lgkmcnt(1)
	v_mfma_f32_32x32x16_bf16 v[0:15], v[164:167], v[160:163], v[0:15]
	v_cvt_pk_bf16_f32 v160, v56, v57
	v_cvt_pk_bf16_f32 v161, v58, v59
	v_cvt_pk_bf16_f32 v162, v60, v61
	v_cvt_pk_bf16_f32 v163, v62, v63
	ds_read2_b64 v[164:167], v155 offset0:68 offset1:70
	v_sub_f32_e32 v34, v34, v153
	v_sub_f32_e32 v35, v35, v153
	s_waitcnt lgkmcnt(1)
	v_mfma_f32_32x32x16_bf16 v[16:31], v[156:159], v[160:163], v[16:31]
	ds_read2_b64 v[156:159], v168 offset0:8 offset1:10
	v_sub_f32_e32 v36, v36, v153
	v_sub_f32_e32 v37, v37, v153
	v_sub_f32_e32 v38, v38, v153
	v_sub_f32_e32 v39, v39, v153
	v_exp_f32_e32 v32, v32
	v_exp_f32_e32 v33, v33
	v_exp_f32_e32 v34, v34
	v_exp_f32_e32 v35, v35
	v_exp_f32_e32 v36, v36
	v_exp_f32_e32 v37, v37
	v_exp_f32_e32 v38, v38
	v_exp_f32_e32 v39, v39
	s_waitcnt lgkmcnt(1)
	v_mfma_f32_32x32x16_bf16 v[0:15], v[164:167], v[160:163], v[0:15]
	v_cvt_pk_bf16_f32 v160, v32, v33
	v_cvt_pk_bf16_f32 v161, v34, v35
	v_cvt_pk_bf16_f32 v162, v36, v37
	v_cvt_pk_bf16_f32 v163, v38, v39
	ds_read2_b64 v[164:167], v155 offset0:72 offset1:74
	v_sub_f32_e32 v40, v40, v153
	v_sub_f32_e32 v41, v41, v153
	s_waitcnt lgkmcnt(1)
	v_mfma_f32_32x32x16_bf16 v[16:31], v[156:159], v[160:163], v[16:31]
	ds_read2_b64 v[156:159], v168 offset0:12 offset1:14
	v_sub_f32_e32 v42, v42, v153
	v_sub_f32_e32 v43, v43, v153
	v_sub_f32_e32 v44, v44, v153
	v_sub_f32_e32 v45, v45, v153
	v_sub_f32_e32 v46, v46, v153
	v_sub_f32_e32 v47, v47, v153
	v_exp_f32_e32 v40, v40
	v_exp_f32_e32 v41, v41
	v_exp_f32_e32 v42, v42
	v_exp_f32_e32 v43, v43
	v_exp_f32_e32 v44, v44
	v_exp_f32_e32 v45, v45
	v_exp_f32_e32 v46, v46
	v_exp_f32_e32 v47, v47
	s_waitcnt lgkmcnt(1)
	v_mfma_f32_32x32x16_bf16 v[0:15], v[164:167], v[160:163], v[0:15]
	v_cvt_pk_bf16_f32 v160, v40, v41
	v_cvt_pk_bf16_f32 v161, v42, v43
	v_cvt_pk_bf16_f32 v162, v44, v45
	v_cvt_pk_bf16_f32 v163, v46, v47
	s_waitcnt lgkmcnt(0)
	s_nop 0
	v_mfma_f32_32x32x16_bf16 v[16:31], v[156:159], v[160:163], v[16:31]
	ds_read2_b64 v[156:159], v155 offset0:76 offset1:78
	s_waitcnt lgkmcnt(0)
	v_mfma_f32_32x32x16_bf16 v[0:15], v[156:159], v[160:163], v[0:15]
	s_cbranch_vccnz .LBB0_779
	s_xor_b32 s0, s4, 1
	s_mulk_i32 s0, 0x2400
	s_add_i32 s1, s0, 0
	v_add3_u32 v155, s1, v121, v122
	s_waitcnt vmcnt(3)
	ds_write_b128 v155, v[80:83]
	v_add3_u32 v155, s1, v124, v125
	s_waitcnt vmcnt(2)
	ds_write_b128 v155, v[84:87]
	v_add_u32_e32 v155, s0, v126
	v_lshl_add_u32 v156, v115, 1, v155
	v_lshl_add_u32 v155, v120, 1, v155
	s_waitcnt vmcnt(1)
	ds_write_b16 v156, v88 offset:18432
	ds_write_b16_d16_hi v156, v88 offset:18576
	ds_write_b16 v156, v89 offset:18720
	ds_write_b16_d16_hi v156, v89 offset:18864
	ds_write_b16 v156, v90 offset:19008
	ds_write_b16_d16_hi v156, v90 offset:19152
	ds_write_b16 v156, v91 offset:19296
	ds_write_b16_d16_hi v156, v91 offset:19440
	s_waitcnt vmcnt(0)
	ds_write_b16 v155, v92 offset:18432
	ds_write_b16_d16_hi v155, v92 offset:18576
	ds_write_b16 v155, v93 offset:18720
	ds_write_b16_d16_hi v155, v93 offset:18864
	ds_write_b16 v155, v94 offset:19008
	ds_write_b16_d16_hi v155, v94 offset:19152
	ds_write_b16 v155, v95 offset:19296
	ds_write_b16_d16_hi v155, v95 offset:19440

; DI float silu_f(float x) { return x * __builtin_amdgcn_rcpf(1.f + __expf(-x)); }
; DI void scan_post(const P& p, int layer, int vb, int nvb) {
;     ...
;   for (int t = vb * 4 + wave; t < nrows; t += nvb * 4) {
;     float a[8], bb[8], gt[8];
;     unpack8(*(const uint4*)(o0 + (size_t)t * 512 + lane * 8), a);
;     unpack8(*(const uint4*)(o1 + (size_t)t * 512 + lane * 8), bb);
;     unpack8(*(const uint4*)(z + (size_t)t * ldz + goff + lane * 8), gt);
;     float ss = 0.f;
; #pragma unroll
;     for (int j = 0; j < 8; ++j) { a[j] += bb[j]; ss += a[j] * a[j]; }
;     ss += __shfl_xor(ss, 1); ss += __shfl_xor(ss, 2); ss += __shfl_xor(ss, 4);
;     float rms;
;     if (layer == 0) rms = rsqrtf(ss * (1.f / 64.f) + EPS);
;     else { ss += __shfl_xor(ss, 8); rms = rsqrtf(ss * (1.f / 128.f) + EPS); }
; #pragma unroll
;     for (int j = 0; j < 8; ++j) a[j] = a[j] * rms * on[j] * silu_f(gt[j]);
;     *(uint4*)(o0 + (size_t)t * 512 + lane * 8) = pack8(a);
.LBB0_822:
	v_lshl_add_u64 v[24:25], v[10:11], 0, v[8:9]
	v_add_co_u32_e32 v26, vcc, 0xf172000, v24
	v_add_u32_e32 v14, s16, v14
	s_nop 0
	v_addc_co_u32_e32 v27, vcc, 0, v25, vcc
	global_load_dwordx4 v[20:23], v[26:27], off
	v_add_co_u32_e32 v232, vcc, s49, v24
	s_nop 1
	v_addc_co_u32_e32 v233, vcc, 0, v25, vcc
	global_load_dwordx4 v[224:227], v[232:233], off
	v_lshl_add_u64 v[232:233], v[12:13], 0, v[8:9]
	global_load_dwordx4 v[228:231], v[232:233], off offset:-8
	v_lshl_add_u64 v[10:11], v[10:11], 0, s[38:39]
	s_waitcnt vmcnt(2)
	v_lshlrev_b32_e32 v28, 16, v20
	v_and_b32_e32 v29, 0xffff0000, v20
	v_lshlrev_b32_e32 v30, 16, v21
	v_and_b32_e32 v31, 0xffff0000, v21
	v_lshlrev_b32_e32 v32, 16, v22
	v_and_b32_e32 v33, 0xffff0000, v22
	v_lshlrev_b32_e32 v34, 16, v23
	v_and_b32_e32 v35, 0xffff0000, v23
	s_waitcnt vmcnt(1)
	v_lshlrev_b32_e32 v24, 16, v224
	v_and_b32_e32 v25, 0xffff0000, v224
	v_lshlrev_b32_e32 v36, 16, v225
	v_and_b32_e32 v37, 0xffff0000, v225
	v_lshlrev_b32_e32 v38, 16, v226
	v_and_b32_e32 v39, 0xffff0000, v226
	v_lshlrev_b32_e32 v40, 16, v227
	v_and_b32_e32 v41, 0xffff0000, v227
	v_pk_add_f32 v[24:25], v[28:29], v[24:25]
	v_pk_add_f32 v[30:31], v[30:31], v[36:37]
	v_pk_mul_f32 v[28:29], v[24:25], v[24:25]
	v_pk_mul_f32 v[36:37], v[30:31], v[30:31]
	v_pk_add_f32 v[32:33], v[32:33], v[38:39]
	v_pk_add_f32 v[34:35], v[34:35], v[40:41]
	v_pk_mul_f32 v[38:39], v[32:33], v[32:33]
	v_pk_mul_f32 v[40:41], v[34:35], v[34:35]
	v_lshl_add_u64 v[12:13], v[12:13], 0, s[18:19]
	s_waitcnt vmcnt(0)
	v_lshlrev_b32_e32 v44, 16, v230
	v_mul_f32_e32 v19, 0xbfb8aa3b, v44
	v_exp_f32_e32 v19, v19
	v_and_b32_e32 v45, 0xffff0000, v230
	v_lshlrev_b32_e32 v42, 16, v228
	v_and_b32_e32 v43, 0xffff0000, v228
	v_add_f32_e32 v19, 1.0, v19
	v_rcp_f32_e32 v46, v19
	v_mul_f32_e32 v19, 0xbfb8aa3b, v45
	v_exp_f32_e32 v19, v19
	v_lshlrev_b32_e32 v20, 16, v229
	v_and_b32_e32 v21, 0xffff0000, v229
	v_lshlrev_b32_e32 v22, 16, v231
	v_add_f32_e32 v19, 1.0, v19
	v_rcp_f32_e32 v47, v19
	v_mul_f32_e32 v19, 0xbfb8aa3b, v20
	v_exp_f32_e32 v19, v19
	v_and_b32_e32 v23, 0xffff0000, v231
	v_pk_mul_f32 v[44:45], v[46:47], v[44:45]
	v_add_f32_e32 v19, 1.0, v19
	v_rcp_f32_e32 v46, v19
	v_mul_f32_e32 v19, 0xbfb8aa3b, v21
	v_exp_f32_e32 v19, v19
	s_nop 0
	v_add_f32_e32 v19, 1.0, v19
	v_rcp_f32_e32 v47, v19
	v_mul_f32_e32 v19, 0xbfb8aa3b, v42
	v_exp_f32_e32 v19, v19
	v_pk_mul_f32 v[20:21], v[46:47], v[20:21]
	v_add_f32_e32 v19, 1.0, v19
	v_rcp_f32_e32 v46, v19
	v_mul_f32_e32 v19, 0xbfb8aa3b, v43
	v_exp_f32_e32 v19, v19
	s_nop 0
	v_add_f32_e32 v19, 1.0, v19
	v_rcp_f32_e32 v47, v19
	v_add_f32_e32 v19, v28, v29
	v_add_f32_e32 v19, v19, v36
	v_add_f32_e32 v19, v37, v19
	v_add_f32_e32 v19, v38, v19
	v_add_f32_e32 v19, v39, v19
	v_add_f32_e32 v19, v40, v19
	v_add_f32_e32 v19, v41, v19
	v_pk_mul_f32 v[42:43], v[46:47], v[42:43]
	s_nop 1
	v_add_f32_dpp v19, v19, v19 quad_perm:[1,0,3,2] row_mask:0xf bank_mask:0xf
	s_nop 1
	v_add_f32_dpp v19, v19, v19 quad_perm:[2,3,0,1] row_mask:0xf bank_mask:0xf
	s_nop 1
	v_add_f32_dpp v19, v19, v19 row_half_mirror row_mask:0xf bank_mask:0xf
	s_nop 1
	v_add_f32_dpp v19, v19, v19 row_mirror row_mask:0xf bank_mask:0xf
	v_fmamk_f32 v19, v19, 0x3c000000, v119
	v_cmp_gt_f32_e32 vcc, s9, v19
	v_mul_f32_e32 v28, 0x4b800000, v19
	s_nop 0
	v_cndmask_b32_e32 v19, v19, v28, vcc
	v_rsq_f32_e32 v19, v19
	s_nop 0
	v_mul_f32_e32 v28, 0x45800000, v19
	v_cndmask_b32_e32 v28, v19, v28, vcc
	v_mul_f32_e32 v19, 0xbfb8aa3b, v22
	v_exp_f32_e32 v19, v19
	v_pk_mul_f32 v[30:31], v[30:31], v[28:29] op_sel_hi:[1,0]
	v_pk_mul_f32 v[24:25], v[24:25], v[28:29] op_sel_hi:[1,0]
	v_pk_mul_f32 v[30:31], v[6:7], v[30:31]
	v_add_f32_e32 v19, 1.0, v19
	v_pk_mul_f32 v[30:31], v[20:21], v[30:31]
	v_pk_mul_f32 v[20:21], v[32:33], v[28:29] op_sel_hi:[1,0]
	v_pk_mul_f32 v[28:29], v[34:35], v[28:29] op_sel_hi:[1,0]
	v_pk_mul_f32 v[20:21], v[0:1], v[20:21]
	v_pk_mul_f32 v[24:25], v[4:5], v[24:25]
	v_pk_mul_f32 v[32:33], v[44:45], v[20:21]
	v_rcp_f32_e32 v20, v19
	v_mul_f32_e32 v19, 0xbfb8aa3b, v23
	v_exp_f32_e32 v19, v19
	v_pk_mul_f32 v[28:29], v[2:3], v[28:29]
	v_pk_mul_f32 v[24:25], v[42:43], v[24:25]
	v_cmp_lt_i32_e32 vcc, s46, v14
	v_add_f32_e32 v19, 1.0, v19
	v_rcp_f32_e32 v21, v19
	s_or_b64 s[4:5], vcc, s[4:5]
	v_pk_mul_f32 v[20:21], v[20:21], v[22:23]
	s_nop 0
	v_pk_mul_f32 v[28:29], v[20:21], v[28:29]
	v_cvt_pk_bf16_f32 v20, v24, v25
	v_cvt_pk_bf16_f32 v21, v30, v31
	v_cvt_pk_bf16_f32 v22, v32, v33
	v_cvt_pk_bf16_f32 v23, v28, v29
	global_store_dwordx4 v[26:27], v[20:23], off
	s_andn2_b64 exec, exec, s[4:5]
	s_cbranch_execnz .LBB0_822

; DI void mla_finalize(const P& p, char* smem, int vb, int nvb) {
;     ...
;     float ssq = 0.f, sskv = 0.f;
;     if (lane < 48) {
;       uint4 v = *(const uint4*)(z + (size_t)t * EVEN_IN + lane * 8);
;       unpack8(v, f);
; #pragma unroll
;       for (int j = 0; j < 8; ++j) ssq += f[j] * f[j];
;     }
;     if (lane < 32) {
;       uint4 v = *(const uint4*)(z + (size_t)t * EVEN_IN + 384 + lane * 8);
;       unpack8(v, f);
; #pragma unroll
;       for (int j = 0; j < 8; ++j) sskv += f[j] * f[j];
;     }
;     ssq = wave_sum(ssq);
;     sskv = wave_sum(sskv);
;     const float rq = rsqrtf(ssq * (1.f / 384.f) + EPS), rkv = rsqrtf(sskv * (1.f / 256.f) + EPS);
.LBB0_1044:
	s_or_b64 exec, exec, s[44:45]
	v_cmp_gt_i32_e64 s[44:45], s8, v72
	v_mov_b32_e32 v67, 1.0
	v_mov_b32_e32 v69, 0
	v_add_f32_dpp v52, v52, v52 quad_perm:[1,0,3,2] row_mask:0xf bank_mask:0xf
	v_add_f32_dpp v53, v53, v53 quad_perm:[1,0,3,2] row_mask:0xf bank_mask:0xf
	s_nop 0
	v_add_f32_dpp v52, v52, v52 quad_perm:[2,3,0,1] row_mask:0xf bank_mask:0xf
	v_add_f32_dpp v53, v53, v53 quad_perm:[2,3,0,1] row_mask:0xf bank_mask:0xf
	s_nop 0
	v_add_f32_dpp v52, v52, v52 row_half_mirror row_mask:0xf bank_mask:0xf
	v_add_f32_dpp v53, v53, v53 row_half_mirror row_mask:0xf bank_mask:0xf
	s_nop 0
	v_add_f32_dpp v52, v52, v52 row_mirror row_mask:0xf bank_mask:0xf
	v_add_f32_dpp v53, v53, v53 row_mirror row_mask:0xf bank_mask:0xf
	s_nop 0
	v_add_f32_dpp v52, v52, v52 row_bcast:15 row_mask:0xa bank_mask:0xf
	v_add_f32_dpp v53, v53, v53 row_bcast:15 row_mask:0xa bank_mask:0xf
	s_nop 0
	v_add_f32_dpp v52, v52, v52 row_bcast:31 row_mask:0xc bank_mask:0xf
	v_add_f32_dpp v53, v53, v53 row_bcast:31 row_mask:0xc bank_mask:0xf
	s_nop 0
	s_nop 0
	v_readlane_b32 s100, v52, 63
	v_readlane_b32 s101, v53, 63
	s_nop 3
	v_mov_b32_e32 v52, s100
	v_mov_b32_e32 v53, s101
	s_and_saveexec_b64 s[46:47], s[44:45]
	s_cbranch_execz .LBB0_1046
	v_and_b32_e32 v56, 63, v72
	v_bfe_u32 v57, v72, 6, 5
	v_cndmask_b32_e64 v56, v56, v57, s[40:41]
	v_cvt_f32_ubyte0_e32 v56, v56
	v_mul_f32_e32 v56, v81, v56
	v_mul_f32_e32 v57, 0.15915494, v56
	v_floor_f32_e32 v57, v57
	v_fma_f32 v56, v56, 0.15915494, -v57
	v_cos_f32_e32 v67, v56
	v_sin_f32_e32 v69, v56
.LBB0_1046:
	s_or_b64 exec, exec, s[46:47]
	s_mov_b32 s16, 0x3b800000
	s_waitcnt lgkmcnt(0)
	v_mov_b64_e32 v[70:71], s[2:3]
	s_mov_b32 s17, 0x3b2aaaab
	v_pk_fma_f32 v[52:53], v[52:53], s[16:17], v[70:71] op_sel_hi:[1,1,0]
	s_waitcnt lgkmcnt(0)
	ds_read2_b32 v[60:61], v86 offset1:8
	ds_read2_b32 v[62:63], v86 offset0:16 offset1:24
	ds_read2_b32 v[64:65], v86 offset0:32 offset1:40
	ds_read2_b32 v[88:89], v86 offset0:48 offset1:56
	ds_read2_b32 v[90:91], v86 offset0:64 offset1:72
	ds_read2_b32 v[92:93], v86 offset0:80 offset1:88
	v_mul_f32_e32 v54, 0x4b800000, v53
	v_cmp_gt_f32_e32 vcc, s9, v53
	v_cmp_gt_f32_e64 s[46:47], s9, v52
	s_mov_b32 s16, 0x3c2aaaab
	v_cndmask_b32_e32 v53, v53, v54, vcc
	v_mul_f32_e32 v54, 0x4b800000, v52
	v_rsq_f32_e32 v53, v53
	v_cndmask_b32_e64 v52, v52, v54, s[46:47]
	v_rsq_f32_e32 v52, v52
	ds_bpermute_b32 v66, v82, v67
	v_mul_f32_e32 v54, 0x45800000, v53
	v_cndmask_b32_e32 v58, v53, v54, vcc
	v_mul_f32_e32 v53, 0x45800000, v52
	v_cndmask_b32_e64 v52, v52, v53, s[46:47]
	v_add_u32_e32 v53, 0xc00, v85
	ds_read2_b32 v[94:95], v53 offset1:8
	ds_read2_b32 v[98:99], v53 offset0:16 offset1:24
	ds_read2_b32 v[100:101], v53 offset0:32 offset1:40
	ds_read2_b32 v[102:103], v53 offset0:48 offset1:56
	v_add_u32_e32 v53, 0x1c00, v73
	ds_read2_b32 v[54:55], v53 offset1:8
	ds_read2_b32 v[56:57], v53 offset0:16 offset1:24
	s_waitcnt lgkmcnt(8)
	v_pk_mul_f32 v[90:91], v[58:59], v[90:91] op_sel_hi:[0,1]
	s_waitcnt lgkmcnt(7)
	v_pk_mul_f32 v[92:93], v[58:59], v[92:93] op_sel_hi:[0,1]
	v_pk_mul_f32 v[108:109], v[58:59], v[60:61] op_sel_hi:[0,1]
	v_pk_mul_f32 v[120:121], v[58:59], v[62:63] op_sel_hi:[0,1]
	v_pk_mul_f32 v[122:123], v[58:59], v[64:65] op_sel_hi:[0,1]
	v_pk_mul_f32 v[88:89], v[58:59], v[88:89] op_sel_hi:[0,1]
	s_waitcnt lgkmcnt(1)
	v_mov_b32_e32 v58, v55
	v_mov_b32_e32 v59, v54
	v_pk_mul_f32 v[126:127], v[58:59], v[58:59]
	s_waitcnt lgkmcnt(0)
; DI void mla_finalize(const P& p, char* smem, int vb, int nvb) {
;     ...
;     const float c0 = __shfl(cs, sub), s0 = __shfl(sn, sub), c1 = __shfl(cs, sub + 8), s1 = __shfl(sn, sub + 8);
;     wave_lds_sync();
;     float y[12];
;     float ss = 0.f;
; #pragma unroll
;     for (int j = 0; j < 12; ++j) { y[j] = sq[h * 96 + sub + 8 * j] * rq; ss += y[j] * y[j]; }
;     ss += __shfl_xor(ss, 1); ss += __shfl_xor(ss, 2); ss += __shfl_xor(ss, 4);
;     float rms = rsqrtf(ss * (1.f / 96.f) + EPS);
; #pragma unroll
;     for (int j = 0; j < 12; ++j) y[j] *= rms * qn[j];
;     if (lat) {
;       const float a8 = y[8] * c0 - y[10] * s0, a10 = y[8] * s0 + y[10] * c0;
;       const float a9 = y[9] * c1 - y[11] * s1, a11 = y[9] * s1 + y[11] * c1;
;       y[8] = a8; y[10] = a10; y[9] = a9; y[11] = a11;
;     }
;     float kk[12];
;     float ssk = 0.f;
; #pragma unroll
;     for (int j = 0; j < 12; ++j) {
;       kk[j] = j < 8 ? skv[h * 128 + sub + 8 * j] * rkv : skr[sub + 8 * j - 64];
;       ssk += kk[j] * kk[j];
;     }
;     ssk += __shfl_xor(ssk, 1); ssk += __shfl_xor(ssk, 2); ssk += __shfl_xor(ssk, 4);
;     rms = rsqrtf(ssk * (1.f / 96.f) + EPS);
; #pragma unroll
;     for (int j = 0; j < 12; ++j) kk[j] *= rms * kn[j];
;     if (lat) {
;       const float a8 = kk[8] * c0 - kk[10] * s0, a10 = kk[8] * s0 + kk[10] * c0;
;       const float a9 = kk[9] * c1 - kk[11] * s1, a11 = kk[9] * s1 + kk[11] * c1;
;       kk[8] = a8; kk[10] = a10; kk[9] = a9; kk[11] = a11;
;     }
;     wave_lds_sync();
; #pragma unroll
;     for (int j = 0; j < 12; ++j) sq[h * 96 + sub + 8 * j] = y[j] * QSCALE;
;     wave_lds_sync();
;     {
;       *(uint4*)(Q + (size_t)t * 768 + lane * 8) = pack8(sq + lane * 8);
;       if (lane < 32) *(uint4*)(Q + (size_t)t * 768 + (lane + 64) * 8) = pack8(sq + (lane + 64) * 8);
	v_mov_b32_e32 v58, v57
	v_mov_b32_e32 v59, v56
	v_pk_mul_f32 v[62:63], v[52:53], v[94:95] op_sel_hi:[0,1]
	v_pk_mul_f32 v[128:129], v[58:59], v[58:59]
	v_pk_mul_f32 v[58:59], v[52:53], v[100:101] op_sel_hi:[0,1]
	v_mov_b32_e32 v100, v63
	v_mov_b32_e32 v101, v109
	v_pk_mul_f32 v[60:61], v[52:53], v[98:99] op_sel_hi:[0,1]
	v_mov_b32_e32 v98, v62
	v_mov_b32_e32 v99, v108
	v_pk_mul_f32 v[100:101], v[100:101], v[100:101]
	v_pk_mul_f32 v[64:65], v[122:123], v[122:123]
	v_pk_fma_f32 v[98:99], v[98:99], v[98:99], v[100:101]
	v_mov_b32_e32 v100, v60
	v_mov_b32_e32 v101, v120
	v_pk_mul_f32 v[94:95], v[58:59], v[58:59]
	v_mov_b32_e32 v130, v61
	v_mov_b32_e32 v131, v121
	v_pk_fma_f32 v[98:99], v[100:101], v[100:101], v[98:99]
	v_mov_b32_e32 v100, v94
	v_pk_fma_f32 v[98:99], v[130:131], v[130:131], v[98:99]
	v_mov_b32_e32 v101, v64
	v_pk_add_f32 v[98:99], v[98:99], v[100:101]
	v_mov_b32_e32 v64, v95
	v_pk_add_f32 v[94:95], v[98:99], v[64:65]
	v_pk_mul_f32 v[64:65], v[52:53], v[102:103] op_sel_hi:[0,1]
	v_pk_mul_f32 v[124:125], v[88:89], v[88:89]
	v_pk_mul_f32 v[98:99], v[64:65], v[64:65]
	v_mov_b32_e32 v101, v124
	v_mov_b32_e32 v100, v98
	v_pk_mul_f32 v[104:105], v[90:91], v[90:91]
	v_pk_add_f32 v[94:95], v[94:95], v[100:101]
	v_mov_b32_e32 v124, v99
	v_pk_add_f32 v[94:95], v[94:95], v[124:125]
	v_pk_mov_b32 v[98:99], v[126:127], v[104:105] op_sel:[1,0]
	v_pk_mul_f32 v[106:107], v[92:93], v[92:93]
	v_pk_add_f32 v[94:95], v[98:99], v[94:95]
	v_mov_b32_e32 v127, v105
	v_pk_add_f32 v[94:95], v[126:127], v[94:95]
	v_pk_mov_b32 v[98:99], v[128:129], v[106:107] op_sel:[1,0]
	v_mov_b32_e32 v129, v107
	v_pk_add_f32 v[94:95], v[98:99], v[94:95]
	ds_bpermute_b32 v68, v82, v69
	v_pk_add_f32 v[94:95], v[128:129], v[94:95]
	ds_bpermute_b32 v99, v80, v95
	ds_bpermute_b32 v98, v80, v94
	ds_bpermute_b32 v67, v83, v67
	ds_bpermute_b32 v69, v83, v69
	s_waitcnt lgkmcnt(0)
	s_waitcnt lgkmcnt(2)
	v_pk_add_f32 v[94:95], v[94:95], v[98:99]
	ds_bpermute_b32 v99, v79, v95
	ds_bpermute_b32 v98, v79, v94
	s_waitcnt lgkmcnt(0)
	v_pk_add_f32 v[94:95], v[94:95], v[98:99]
	ds_bpermute_b32 v99, v78, v95
	ds_bpermute_b32 v98, v78, v94
	s_waitcnt lgkmcnt(0)
	v_pk_add_f32 v[94:95], v[94:95], v[98:99]
	s_nop 0
	v_pk_fma_f32 v[70:71], v[94:95], s[16:17], v[70:71] op_sel_hi:[1,0,0]
	s_mov_b64 s[16:17], 0xbb72000
	v_mul_f32_e32 v53, 0x4b800000, v71
	v_cmp_gt_f32_e32 vcc, s9, v71
	v_cmp_gt_f32_e64 s[46:47], s9, v70
	s_nop 0
	v_cndmask_b32_e32 v53, v71, v53, vcc
	v_rsq_f32_e32 v53, v53
	s_nop 0
	v_mul_f32_e32 v71, 0x45800000, v53
	v_cndmask_b32_e32 v94, v53, v71, vcc
	v_pk_mul_f32 v[104:105], v[32:33], v[94:95] op_sel_hi:[1,0]
	v_pk_mul_f32 v[98:99], v[38:39], v[94:95] op_sel_hi:[1,0]
	v_pk_mul_f32 v[100:101], v[36:37], v[94:95] op_sel_hi:[1,0]
	v_pk_mul_f32 v[102:103], v[34:35], v[94:95] op_sel_hi:[1,0]
	v_pk_mul_f32 v[88:89], v[88:89], v[104:105]
	v_pk_mul_f32 v[104:105], v[22:23], v[94:95] op_sel_hi:[1,0]
	v_pk_mul_f32 v[94:95], v[16:17], v[94:95] op_sel_hi:[1,0]
	v_pk_mul_f32 v[90:91], v[90:91], v[104:105]
	v_pk_mul_f32 v[92:93], v[92:93], v[94:95]
	v_pk_mul_f32 v[98:99], v[108:109], v[98:99]
	v_pk_mul_f32 v[94:95], v[92:93], v[68:69]
	v_pk_mul_f32 v[104:105], v[92:93], v[66:67]
	v_pk_fma_f32 v[94:95], v[90:91], v[66:67], v[94:95] neg_lo:[0,0,1] neg_hi:[0,0,1]
	v_pk_fma_f32 v[104:105], v[90:91], v[68:69], v[104:105]
	v_pk_mul_f32 v[100:101], v[120:121], v[100:101]
	v_cndmask_b32_e64 v71, v92, v104, s[44:45]
	v_cndmask_b32_e64 v87, v91, v95, s[44:45]
	v_mul_f32_e32 v91, 0x3e16c740, v98
	v_mul_f32_e32 v92, 0x3e16c740, v99
	v_pk_mul_f32 v[102:103], v[122:123], v[102:103]
	v_cndmask_b32_e64 v53, v93, v105, s[44:45]
	v_cndmask_b32_e64 v90, v90, v94, s[44:45]
	ds_write2_b32 v86, v91, v92 offset1:8
	v_mul_f32_e32 v91, 0x3e16c740, v100
	v_mul_f32_e32 v92, 0x3e16c740, v101
	v_mul_f32_e32 v88, 0x3e16c740, v88
	v_mul_f32_e32 v89, 0x3e16c740, v89
	ds_write2_b32 v86, v91, v92 offset0:16 offset1:24
	v_mul_f32_e32 v91, 0x3e16c740, v102
	v_mul_f32_e32 v92, 0x3e16c740, v103
	ds_write2_b32 v86, v88, v89 offset0:48 offset1:56
	v_mul_f32_e32 v88, 0x3e16c740, v90
	v_mul_f32_e32 v87, 0x3e16c740, v87
	v_mul_f32_e32 v71, 0x3e16c740, v71
	v_mul_f32_e32 v53, 0x3e16c740, v53
	ds_write2_b32 v86, v91, v92 offset0:32 offset1:40
	ds_write2_b32 v86, v88, v87 offset0:64 offset1:72
	ds_write2_b32 v86, v71, v53 offset0:80 offset1:88
	s_waitcnt lgkmcnt(0)
	ds_read_b128 v[88:91], v74
	ds_read_b128 v[92:95], v74 offset:16
	v_lshl_add_u64 v[98:99], v[48:49], 0, s[16:17]
	s_waitcnt lgkmcnt(1)
	v_cvt_pk_bf16_f32 v88, v88, v89
	v_cvt_pk_bf16_f32 v89, v90, v91
	s_waitcnt lgkmcnt(0)
	v_cvt_pk_bf16_f32 v90, v92, v93
	v_cvt_pk_bf16_f32 v91, v94, v95
	global_store_dwordx4 v[98:99], v[88:91], off
	s_and_saveexec_b64 s[52:53], s[0:1]
	s_cbranch_execz .LBB0_1048
	ds_read_b128 v[88:91], v74 offset:2048
	ds_read_b128 v[92:95], v74 offset:2064
	s_waitcnt lgkmcnt(1)
	v_cvt_pk_bf16_f32 v88, v88, v89
	v_cvt_pk_bf16_f32 v89, v90, v91
	s_waitcnt lgkmcnt(0)
	v_cvt_pk_bf16_f32 v90, v92, v93
	v_add_co_u32_e32 v92, vcc, 0xbb72000, v48
	v_cvt_pk_bf16_f32 v91, v94, v95
	s_nop 0
	v_addc_co_u32_e32 v93, vcc, 0, v49, vcc
	global_store_dwordx4 v[92:93], v[88:91], off offset:1024

; template <int DQK, bool SWA> ...
;     ...
;     f32x16 s[2];
; #pragma unroll
;     for (int mt = 0; mt < 2; ++mt) {
; #pragma unroll
;       for (int i = 0; i < 16; ++i) s[mt][i] = 0.f;
;       const u16* kb = Ks + buf * 64 * KSTR + (mt * 32 + r) * KSTR + hh * 8;
; #pragma unroll
;       for (int ks = 0; ks < NKS; ++ks) {
;         const bf16x8 a = *(const bf16x8*)(kb + ks * 16);
;         s[mt] = MFMA(a, bq[ks], s[mt]);
;       }
;     }
;     if (SWA && it >= 4) {
;       const int kpos0 = (kt_lo + it - 4) * 64;
;       const int qpos = qpos0 + wave * 32 + r;
; #pragma unroll
;       for (int mt = 0; mt < 2; ++mt)
; #pragma unroll
;         for (int i = 0; i < 16; ++i) {
;           const int kpos = kpos0 + mt * 32 + (i & 3) + 8 * (i >> 2) + 4 * hh;
;           const int dlt = kpos - qpos;
;           if (dlt > 128 || dlt < -128) s[mt][i] = -INFINITY;
;         }
;     }
;     float mx = -INFINITY;
; #pragma unroll
;     for (int mt = 0; mt < 2; ++mt)
; #pragma unroll
;       for (int i = 0; i < 16; ++i) mx = fmaxf(mx, s[mt][i]);
;     mx = fmaxf(mx, __shfl_xor(mx, 32));
;     const float mnew = fmaxf(m, mx);
;     const float alpha = __builtin_amdgcn_exp2f(m - mnew);
;     m = mnew;
;     float psum = 0.f;
; #pragma unroll
;     for (int mt = 0; mt < 2; ++mt)
; #pragma unroll
;       for (int i = 0; i < 16; ++i) {
;         const float pv = __builtin_amdgcn_exp2f(s[mt][i] - mnew);
;         s[mt][i] = pv;
;         psum += pv;
;       }
;     lsum = lsum * alpha + psum;
; #pragma unroll
;     for (int a = 0; a < 2; ++a)
; #pragma unroll
;       for (int i = 0; i < 16; ++i) o[a][i] *= alpha;
; #pragma unroll
;     for (int mt = 0; mt < 2; ++mt)
; #pragma unroll
;       for (int sx = 0; sx < 2; ++sx) {
;         uint4 pu;
;         pu.x = pack2(s[mt][8 * sx + 0], s[mt][8 * sx + 1]);
;         pu.y = pack2(s[mt][8 * sx + 2], s[mt][8 * sx + 3]);
;         pu.z = pack2(s[mt][8 * sx + 4], s[mt][8 * sx + 5]);
;         pu.w = pack2(s[mt][8 * sx + 6], s[mt][8 * sx + 7]);
;         const bf16x8 pfv = __builtin_bit_cast(bf16x8, pu);
; #pragma unroll
;         for (int dt = 0; dt < 2; ++dt) {
;           const u16* vp = Vt + buf * 64 * VSTR + (dt * 32 + r) * VSTR + mt * 32 + 16 * sx + 4 * hh;
;           const uint2 v0 = *(const uint2*)(vp);
;           const uint2 v1 = *(const uint2*)(vp + 8);
;           const uint4 vu = make_uint4(v0.x, v0.y, v1.x, v1.y);
.LBB0_1184:
	s_and_b32 s18, s17, 1
	s_mul_i32 s19, s18, 0x3400
	v_add3_u32 v171, v160, s19, v163
	ds_read_b128 v[224:227], v171
	ds_read_b128 v[228:231], v171 offset:32
	ds_read_b128 v[232:235], v171 offset:64
	ds_read_b128 v[236:239], v171 offset:96
	ds_read_b128 v[240:243], v171 offset:128
	ds_read_b128 v[244:247], v171 offset:160
	ds_read_b128 v[248:251], v171 offset:6656
	ds_read_b128 v[252:255], v171 offset:6688
	s_mul_i32 s19, s18, 0x2400
	v_add3_u32 v184, v162, s19, v164
	v_add_u32_e32 v185, 0x6800, v184
	v_add_u32_e32 v184, 0x7800, v184
	s_andn2_b64 vcc, exec, s[0:1]
	s_waitcnt lgkmcnt(7)
	v_mfma_f32_32x32x16_bf16 v[48:63], v[224:227], v[64:67], 0
	ds_read_b128 v[224:227], v171 offset:6720
	s_waitcnt lgkmcnt(7)
	v_mfma_f32_32x32x16_bf16 v[48:63], v[228:231], v[68:71], v[48:63]
	ds_read_b128 v[228:231], v171 offset:6752
	s_waitcnt lgkmcnt(7)
	v_mfma_f32_32x32x16_bf16 v[48:63], v[232:235], v[72:75], v[48:63]
	ds_read_b128 v[232:235], v171 offset:6784
	s_waitcnt lgkmcnt(7)
	v_mfma_f32_32x32x16_bf16 v[48:63], v[236:239], v[76:79], v[48:63]
	ds_read_b128 v[236:239], v171 offset:6816
	s_waitcnt lgkmcnt(7)
	v_mfma_f32_32x32x16_bf16 v[48:63], v[240:243], v[80:83], v[48:63]
	s_waitcnt lgkmcnt(6)
	v_mfma_f32_32x32x16_bf16 v[48:63], v[244:247], v[84:87], v[48:63]
	s_waitcnt lgkmcnt(5)
	v_mfma_f32_32x32x16_bf16 v[32:47], v[248:251], v[64:67], 0
	s_waitcnt lgkmcnt(4)
	v_mfma_f32_32x32x16_bf16 v[32:47], v[252:255], v[68:71], v[32:47]
	s_waitcnt lgkmcnt(3)
	v_mfma_f32_32x32x16_bf16 v[32:47], v[224:227], v[72:75], v[32:47]
	v_max3_f32 v171, v48, s22, v49
	v_max3_f32 v171, v171, v50, v51
	s_waitcnt lgkmcnt(2)
	v_mfma_f32_32x32x16_bf16 v[32:47], v[228:231], v[76:79], v[32:47]
	v_max3_f32 v171, v171, v52, v53
	v_max3_f32 v171, v171, v54, v55
	s_waitcnt lgkmcnt(1)
	v_mfma_f32_32x32x16_bf16 v[32:47], v[232:235], v[80:83], v[32:47]
	v_max3_f32 v171, v171, v56, v57
	v_max3_f32 v171, v171, v58, v59
	s_waitcnt lgkmcnt(0)
	v_mfma_f32_32x32x16_bf16 v[32:47], v[236:239], v[84:87], v[32:47]
	v_max3_f32 v171, v171, v60, v61
	v_max3_f32 v171, v171, v62, v63
	ds_read2_b64 v[176:179], v185 offset1:2
	ds_read2_b64 v[180:183], v185 offset0:4 offset1:6
	s_nop 7
	v_max3_f32 v171, v171, v32, v33
	v_max3_f32 v171, v171, v34, v35
	v_max3_f32 v171, v171, v36, v37
	v_max3_f32 v171, v171, v38, v39
	v_max3_f32 v171, v171, v40, v41
	v_max3_f32 v171, v171, v42, v43
	v_max3_f32 v171, v171, v44, v45
	v_max3_f32 v171, v171, v46, v47
	v_mov_b32_e32 v172, v171
	s_nop 1
	v_permlane32_swap_b32 v172, v171
	s_waitcnt lgkmcnt(0)
	v_max3_f32 v171, v130, v171, v172
	v_sub_f32_e32 v130, v130, v171
	v_sub_f32_e32 v48, v48, v171
	v_sub_f32_e32 v49, v49, v171
	v_sub_f32_e32 v50, v50, v171
	v_sub_f32_e32 v51, v51, v171
	v_sub_f32_e32 v52, v52, v171
	v_sub_f32_e32 v53, v53, v171
	v_sub_f32_e32 v54, v54, v171
	v_sub_f32_e32 v55, v55, v171
	v_exp_f32_e32 v130, v130
	v_exp_f32_e32 v48, v48
	v_exp_f32_e32 v49, v49
	v_exp_f32_e32 v50, v50
	v_exp_f32_e32 v51, v51
	v_exp_f32_e32 v52, v52
	v_exp_f32_e32 v53, v53
	v_exp_f32_e32 v54, v54
	v_exp_f32_e32 v55, v55
	v_pk_mul_f32 v[30:31], v[30:31], v[130:131] op_sel_hi:[1,0]
	v_pk_mul_f32 v[28:29], v[28:29], v[130:131] op_sel_hi:[1,0]
	v_pk_mul_f32 v[26:27], v[26:27], v[130:131] op_sel_hi:[1,0]
	v_pk_mul_f32 v[24:25], v[24:25], v[130:131] op_sel_hi:[1,0]
	v_pk_mul_f32 v[22:23], v[22:23], v[130:131] op_sel_hi:[1,0]
	v_pk_mul_f32 v[20:21], v[20:21], v[130:131] op_sel_hi:[1,0]
	v_pk_mul_f32 v[18:19], v[18:19], v[130:131] op_sel_hi:[1,0]
	v_pk_mul_f32 v[16:17], v[16:17], v[130:131] op_sel_hi:[1,0]
	v_cvt_pk_bf16_f32 v172, v48, v49
	v_cvt_pk_bf16_f32 v173, v50, v51
	v_cvt_pk_bf16_f32 v174, v52, v53
	v_cvt_pk_bf16_f32 v175, v54, v55
	v_pk_mul_f32 v[14:15], v[14:15], v[130:131] op_sel_hi:[1,0]
	v_pk_mul_f32 v[12:13], v[12:13], v[130:131] op_sel_hi:[1,0]
	v_mfma_f32_32x32x16_bf16 v[16:31], v[176:179], v[172:175], v[16:31]
	ds_read2_b64 v[176:179], v184 offset0:64 offset1:66
	v_mul_f32_e64 v10, v10, v130
	v_mul_f32_e64 v11, v11, v130
	v_mul_f32_e64 v8, v8, v130
	v_mul_f32_e64 v9, v9, v130
	v_pk_mul_f32 v[6:7], v[6:7], v[130:131] op_sel_hi:[1,0]
	v_pk_mul_f32 v[4:5], v[4:5], v[130:131] op_sel_hi:[1,0]
	v_pk_mul_f32 v[2:3], v[2:3], v[130:131] op_sel_hi:[1,0]
	v_pk_mul_f32 v[0:1], v[0:1], v[130:131] op_sel_hi:[1,0]
	v_sub_f32_e32 v56, v56, v171
	v_sub_f32_e32 v57, v57, v171
	s_waitcnt lgkmcnt(0)
	v_mfma_f32_32x32x16_bf16 v[0:15], v[176:179], v[172:175], v[0:15]
	ds_read2_b64 v[176:179], v184 offset0:68 offset1:70
	v_sub_f32_e32 v58, v58, v171
	v_sub_f32_e32 v59, v59, v171
	v_sub_f32_e32 v60, v60, v171
	v_sub_f32_e32 v61, v61, v171
	v_sub_f32_e32 v62, v62, v171
	v_sub_f32_e32 v63, v63, v171
	v_exp_f32_e32 v56, v56
	v_exp_f32_e32 v57, v57
	v_exp_f32_e32 v58, v58
	v_exp_f32_e32 v59, v59
	v_exp_f32_e32 v60, v60
	v_exp_f32_e32 v61, v61
	v_exp_f32_e32 v62, v62
	v_exp_f32_e32 v63, v63
	v_cvt_pk_bf16_f32 v172, v56, v57
	v_cvt_pk_bf16_f32 v173, v58, v59
	v_cvt_pk_bf16_f32 v174, v60, v61
	v_cvt_pk_bf16_f32 v175, v62, v63
	v_sub_f32_e32 v32, v32, v171
	v_sub_f32_e32 v33, v33, v171
	s_waitcnt lgkmcnt(0)
	v_mfma_f32_32x32x16_bf16 v[0:15], v[176:179], v[172:175], v[0:15]
	ds_read2_b64 v[176:179], v185 offset0:8 offset1:10
	v_sub_f32_e32 v34, v34, v171
	v_sub_f32_e32 v35, v35, v171
	v_sub_f32_e32 v36, v36, v171
	v_sub_f32_e32 v37, v37, v171
	v_sub_f32_e32 v38, v38, v171
	v_sub_f32_e32 v39, v39, v171
	v_mfma_f32_32x32x16_bf16 v[16:31], v[180:183], v[172:175], v[16:31]
	v_exp_f32_e32 v32, v32
	v_exp_f32_e32 v33, v33
	v_exp_f32_e32 v34, v34
	v_exp_f32_e32 v35, v35
	v_exp_f32_e32 v36, v36
	v_exp_f32_e32 v37, v37
	v_exp_f32_e32 v38, v38
	v_exp_f32_e32 v39, v39
	v_cvt_pk_bf16_f32 v172, v32, v33
	v_cvt_pk_bf16_f32 v173, v34, v35
	v_cvt_pk_bf16_f32 v174, v36, v37
	v_cvt_pk_bf16_f32 v175, v38, v39
	v_sub_f32_e32 v40, v40, v171
	v_sub_f32_e32 v41, v41, v171
	s_waitcnt lgkmcnt(0)
	v_mfma_f32_32x32x16_bf16 v[16:31], v[176:179], v[172:175], v[16:31]
	ds_read2_b64 v[176:179], v184 offset0:72 offset1:74
	v_sub_f32_e32 v42, v42, v171
	v_sub_f32_e32 v43, v43, v171
	v_sub_f32_e32 v44, v44, v171
	v_sub_f32_e32 v45, v45, v171
	v_sub_f32_e32 v46, v46, v171
	v_sub_f32_e32 v47, v47, v171
	s_waitcnt lgkmcnt(0)
	v_mfma_f32_32x32x16_bf16 v[0:15], v[176:179], v[172:175], v[0:15]
	ds_read2_b64 v[176:179], v185 offset0:12 offset1:14
	v_exp_f32_e32 v40, v40
	v_exp_f32_e32 v41, v41
	v_exp_f32_e32 v42, v42
	v_exp_f32_e32 v43, v43
	v_exp_f32_e32 v44, v44
	v_exp_f32_e32 v45, v45
	v_exp_f32_e32 v46, v46
	v_exp_f32_e32 v47, v47
	v_cvt_pk_bf16_f32 v172, v40, v41
	v_cvt_pk_bf16_f32 v173, v42, v43
	v_cvt_pk_bf16_f32 v174, v44, v45
	v_cvt_pk_bf16_f32 v175, v46, v47
	s_waitcnt lgkmcnt(0)
	s_nop 0
	v_mfma_f32_32x32x16_bf16 v[16:31], v[176:179], v[172:175], v[16:31]
	ds_read2_b64 v[176:179], v184 offset0:76 offset1:78
	s_waitcnt lgkmcnt(0)
	v_mfma_f32_32x32x16_bf16 v[0:15], v[176:179], v[172:175], v[0:15]
	s_cbranch_vccnz .LBB0_1186
	s_xor_b32 s0, s18, 1
	s_mul_i32 s1, s0, 0x3400
	s_add_i32 s1, s1, 0
	v_add3_u32 v172, s1, v153, v154
	s_waitcnt vmcnt(4)
	ds_write_b128 v172, v[88:91]
	v_add3_u32 v172, s1, v155, v156
	s_waitcnt vmcnt(3)
	ds_write_b128 v172, v[92:95]
	v_add3_u32 v172, s1, v157, v158
	s_mulk_i32 s0, 0x2400
	s_waitcnt vmcnt(2)
	ds_write_b128 v172, v[98:101]
	v_add_u32_e32 v172, s0, v159
	v_lshl_add_u32 v173, v115, 1, v172
	v_lshl_add_u32 v172, v131, 1, v172
	s_waitcnt vmcnt(1)
	ds_write_b16 v173, v102 offset:26624
	ds_write_b16_d16_hi v173, v102 offset:26768
	ds_write_b16 v173, v103 offset:26912
	ds_write_b16_d16_hi v173, v103 offset:27056
	ds_write_b16 v173, v104 offset:27200
	ds_write_b16_d16_hi v173, v104 offset:27344
	ds_write_b16 v173, v105 offset:27488
	ds_write_b16_d16_hi v173, v105 offset:27632
	s_waitcnt vmcnt(0)
	ds_write_b16 v172, v106 offset:26624
	ds_write_b16_d16_hi v172, v106 offset:26768
	ds_write_b16 v172, v107 offset:26912
	ds_write_b16_d16_hi v172, v107 offset:27056
	ds_write_b16 v172, v108 offset:27200
	ds_write_b16_d16_hi v172, v108 offset:27344
	ds_write_b16 v172, v109 offset:27488
	ds_write_b16_d16_hi v172, v109 offset:27632

; template <int DQK, bool SWA> ...
;     ...
;     f32x16 s[2];
; #pragma unroll
;     for (int mt = 0; mt < 2; ++mt) {
; #pragma unroll
;       for (int i = 0; i < 16; ++i) s[mt][i] = 0.f;
;       const u16* kb = Ks + buf * 64 * KSTR + (mt * 32 + r) * KSTR + hh * 8;
; #pragma unroll
;       for (int ks = 0; ks < NKS; ++ks) {
;         const bf16x8 a = *(const bf16x8*)(kb + ks * 16);
;         s[mt] = MFMA(a, bq[ks], s[mt]);
;       }
;     }
;     if (SWA && it >= 4) {
;       const int kpos0 = (kt_lo + it - 4) * 64;
;       const int qpos = qpos0 + wave * 32 + r;
; #pragma unroll
;       for (int mt = 0; mt < 2; ++mt)
; #pragma unroll
;         for (int i = 0; i < 16; ++i) {
;           const int kpos = kpos0 + mt * 32 + (i & 3) + 8 * (i >> 2) + 4 * hh;
;           const int dlt = kpos - qpos;
;           if (dlt > 128 || dlt < -128) s[mt][i] = -INFINITY;
;         }
;     }
;     float mx = -INFINITY;
; #pragma unroll
;     for (int mt = 0; mt < 2; ++mt)
; #pragma unroll
;       for (int i = 0; i < 16; ++i) mx = fmaxf(mx, s[mt][i]);
;     mx = fmaxf(mx, __shfl_xor(mx, 32));
;     const float mnew = fmaxf(m, mx);
;     const float alpha = __builtin_amdgcn_exp2f(m - mnew);
;     m = mnew;
;     float psum = 0.f;
; #pragma unroll
;     for (int mt = 0; mt < 2; ++mt)
; #pragma unroll
;       for (int i = 0; i < 16; ++i) {
;         const float pv = __builtin_amdgcn_exp2f(s[mt][i] - mnew);
;         s[mt][i] = pv;
;         psum += pv;
;       }
;     lsum = lsum * alpha + psum;
; #pragma unroll
;     for (int a = 0; a < 2; ++a)
; #pragma unroll
;       for (int i = 0; i < 16; ++i) o[a][i] *= alpha;
; #pragma unroll
;     for (int mt = 0; mt < 2; ++mt)
; #pragma unroll
;       for (int sx = 0; sx < 2; ++sx) {
;         uint4 pu;
;         pu.x = pack2(s[mt][8 * sx + 0], s[mt][8 * sx + 1]);
;         pu.y = pack2(s[mt][8 * sx + 2], s[mt][8 * sx + 3]);
;         pu.z = pack2(s[mt][8 * sx + 4], s[mt][8 * sx + 5]);
;         pu.w = pack2(s[mt][8 * sx + 6], s[mt][8 * sx + 7]);
;         const bf16x8 pfv = __builtin_bit_cast(bf16x8, pu);
; #pragma unroll
;         for (int dt = 0; dt < 2; ++dt) {
;           const u16* vp = Vt + buf * 64 * VSTR + (dt * 32 + r) * VSTR + mt * 32 + 16 * sx + 4 * hh;
;           const uint2 v0 = *(const uint2*)(vp);
;           const uint2 v1 = *(const uint2*)(vp + 8);
;           const uint4 vu = make_uint4(v0.x, v0.y, v1.x, v1.y);
.LBB0_1192:
	s_and_b32 s18, s15, 1
	s_mul_i32 s19, s18, 0x3400
	v_add3_u32 v169, v163, s19, v166
	ds_read_b128 v[224:227], v169
	ds_read_b128 v[228:231], v169 offset:32
	ds_read_b128 v[232:235], v169 offset:64
	ds_read_b128 v[236:239], v169 offset:96
	ds_read_b128 v[240:243], v169 offset:128
	ds_read_b128 v[244:247], v169 offset:160
	ds_read_b128 v[248:251], v169 offset:6656
	ds_read_b128 v[252:255], v169 offset:6688
	s_mul_i32 s19, s18, 0x2400
	v_add3_u32 v182, v165, s19, v167
	v_add_u32_e32 v183, 0x6800, v182
	v_add_u32_e32 v182, 0x7800, v182
	s_andn2_b64 vcc, exec, s[0:1]
	s_waitcnt lgkmcnt(7)
	v_mfma_f32_32x32x16_bf16 v[48:63], v[224:227], v[64:67], 0
	ds_read_b128 v[224:227], v169 offset:6720
	s_waitcnt lgkmcnt(7)
	v_mfma_f32_32x32x16_bf16 v[48:63], v[228:231], v[68:71], v[48:63]
	ds_read_b128 v[228:231], v169 offset:6752
	s_waitcnt lgkmcnt(7)
	v_mfma_f32_32x32x16_bf16 v[48:63], v[232:235], v[72:75], v[48:63]
	ds_read_b128 v[232:235], v169 offset:6784
	s_waitcnt lgkmcnt(7)
	v_mfma_f32_32x32x16_bf16 v[48:63], v[236:239], v[76:79], v[48:63]
	ds_read_b128 v[236:239], v169 offset:6816
	s_waitcnt lgkmcnt(7)
	v_mfma_f32_32x32x16_bf16 v[48:63], v[240:243], v[80:83], v[48:63]
	s_waitcnt lgkmcnt(6)
	v_mfma_f32_32x32x16_bf16 v[48:63], v[244:247], v[84:87], v[48:63]
	s_waitcnt lgkmcnt(5)
	v_mfma_f32_32x32x16_bf16 v[32:47], v[248:251], v[64:67], 0
	s_waitcnt lgkmcnt(4)
	v_mfma_f32_32x32x16_bf16 v[32:47], v[252:255], v[68:71], v[32:47]
	s_waitcnt lgkmcnt(3)
	v_mfma_f32_32x32x16_bf16 v[32:47], v[224:227], v[72:75], v[32:47]
	v_max3_f32 v169, v48, s22, v49
	v_max3_f32 v169, v169, v50, v51
	s_waitcnt lgkmcnt(2)
	v_mfma_f32_32x32x16_bf16 v[32:47], v[228:231], v[76:79], v[32:47]
	v_max3_f32 v169, v169, v52, v53
	v_max3_f32 v169, v169, v54, v55
	s_waitcnt lgkmcnt(1)
	v_mfma_f32_32x32x16_bf16 v[32:47], v[232:235], v[80:83], v[32:47]
	v_max3_f32 v169, v169, v56, v57
	v_max3_f32 v169, v169, v58, v59
	s_waitcnt lgkmcnt(0)
	v_mfma_f32_32x32x16_bf16 v[32:47], v[236:239], v[84:87], v[32:47]
	v_max3_f32 v169, v169, v60, v61
	v_max3_f32 v169, v169, v62, v63
	ds_read2_b64 v[174:177], v183 offset1:2
	ds_read2_b64 v[178:181], v183 offset0:4 offset1:6
	s_nop 7
	v_max3_f32 v169, v169, v32, v33
	v_max3_f32 v169, v169, v34, v35
	v_max3_f32 v169, v169, v36, v37
	v_max3_f32 v169, v169, v38, v39
	v_max3_f32 v169, v169, v40, v41
	v_max3_f32 v169, v169, v42, v43
	v_max3_f32 v169, v169, v44, v45
	v_max3_f32 v169, v169, v46, v47
	v_mov_b32_e32 v170, v169
	s_nop 1
	v_permlane32_swap_b32 v170, v169
	s_waitcnt lgkmcnt(0)
	v_max3_f32 v169, v130, v169, v170
	v_sub_f32_e32 v130, v130, v169
	v_sub_f32_e32 v48, v48, v169
	v_sub_f32_e32 v49, v49, v169
	v_sub_f32_e32 v50, v50, v169
	v_sub_f32_e32 v51, v51, v169
	v_sub_f32_e32 v52, v52, v169
	v_sub_f32_e32 v53, v53, v169
	v_sub_f32_e32 v54, v54, v169
	v_sub_f32_e32 v55, v55, v169
	v_exp_f32_e32 v130, v130
	v_exp_f32_e32 v48, v48
	v_exp_f32_e32 v49, v49
	v_exp_f32_e32 v50, v50
	v_exp_f32_e32 v51, v51
	v_exp_f32_e32 v52, v52
	v_exp_f32_e32 v53, v53
	v_exp_f32_e32 v54, v54
	v_exp_f32_e32 v55, v55
	v_pk_mul_f32 v[30:31], v[30:31], v[130:131] op_sel_hi:[1,0]
	v_pk_mul_f32 v[28:29], v[28:29], v[130:131] op_sel_hi:[1,0]
	v_pk_mul_f32 v[26:27], v[26:27], v[130:131] op_sel_hi:[1,0]
	v_pk_mul_f32 v[24:25], v[24:25], v[130:131] op_sel_hi:[1,0]
	v_pk_mul_f32 v[22:23], v[22:23], v[130:131] op_sel_hi:[1,0]
	v_pk_mul_f32 v[20:21], v[20:21], v[130:131] op_sel_hi:[1,0]
	v_pk_mul_f32 v[18:19], v[18:19], v[130:131] op_sel_hi:[1,0]
	v_pk_mul_f32 v[16:17], v[16:17], v[130:131] op_sel_hi:[1,0]
	v_cvt_pk_bf16_f32 v170, v48, v49
	v_cvt_pk_bf16_f32 v171, v50, v51
	v_cvt_pk_bf16_f32 v172, v52, v53
	v_cvt_pk_bf16_f32 v173, v54, v55
	v_pk_mul_f32 v[14:15], v[14:15], v[130:131] op_sel_hi:[1,0]
	v_pk_mul_f32 v[12:13], v[12:13], v[130:131] op_sel_hi:[1,0]
	v_mfma_f32_32x32x16_bf16 v[16:31], v[174:177], v[170:173], v[16:31]
	ds_read2_b64 v[174:177], v182 offset0:64 offset1:66
	v_mul_f32_e64 v10, v10, v130
	v_mul_f32_e64 v11, v11, v130
	v_mul_f32_e64 v8, v8, v130
	v_mul_f32_e64 v9, v9, v130
	v_pk_mul_f32 v[6:7], v[6:7], v[130:131] op_sel_hi:[1,0]
	v_pk_mul_f32 v[4:5], v[4:5], v[130:131] op_sel_hi:[1,0]
	v_pk_mul_f32 v[2:3], v[2:3], v[130:131] op_sel_hi:[1,0]
	v_pk_mul_f32 v[0:1], v[0:1], v[130:131] op_sel_hi:[1,0]
	v_sub_f32_e32 v56, v56, v169
	v_sub_f32_e32 v57, v57, v169
	s_waitcnt lgkmcnt(0)
	v_mfma_f32_32x32x16_bf16 v[0:15], v[174:177], v[170:173], v[0:15]
	ds_read2_b64 v[174:177], v182 offset0:68 offset1:70
	v_sub_f32_e32 v58, v58, v169
	v_sub_f32_e32 v59, v59, v169
	v_sub_f32_e32 v60, v60, v169
	v_sub_f32_e32 v61, v61, v169
	v_sub_f32_e32 v62, v62, v169
	v_sub_f32_e32 v63, v63, v169
	v_exp_f32_e32 v56, v56
	v_exp_f32_e32 v57, v57
	v_exp_f32_e32 v58, v58
	v_exp_f32_e32 v59, v59
	v_exp_f32_e32 v60, v60
	v_exp_f32_e32 v61, v61
	v_exp_f32_e32 v62, v62
	v_exp_f32_e32 v63, v63
	v_cvt_pk_bf16_f32 v170, v56, v57
	v_cvt_pk_bf16_f32 v171, v58, v59
	v_cvt_pk_bf16_f32 v172, v60, v61
	v_cvt_pk_bf16_f32 v173, v62, v63
	v_sub_f32_e32 v32, v32, v169
	v_sub_f32_e32 v33, v33, v169
	s_waitcnt lgkmcnt(0)
	v_mfma_f32_32x32x16_bf16 v[0:15], v[174:177], v[170:173], v[0:15]
	ds_read2_b64 v[174:177], v183 offset0:8 offset1:10
	v_sub_f32_e32 v34, v34, v169
	v_sub_f32_e32 v35, v35, v169
	v_sub_f32_e32 v36, v36, v169
	v_sub_f32_e32 v37, v37, v169
	v_sub_f32_e32 v38, v38, v169
	v_sub_f32_e32 v39, v39, v169
	v_mfma_f32_32x32x16_bf16 v[16:31], v[178:181], v[170:173], v[16:31]
	v_exp_f32_e32 v32, v32
	v_exp_f32_e32 v33, v33
	v_exp_f32_e32 v34, v34
	v_exp_f32_e32 v35, v35
	v_exp_f32_e32 v36, v36
	v_exp_f32_e32 v37, v37
	v_exp_f32_e32 v38, v38
	v_exp_f32_e32 v39, v39
	v_cvt_pk_bf16_f32 v170, v32, v33
	v_cvt_pk_bf16_f32 v171, v34, v35
	v_cvt_pk_bf16_f32 v172, v36, v37
	v_cvt_pk_bf16_f32 v173, v38, v39
	v_sub_f32_e32 v40, v40, v169
	v_sub_f32_e32 v41, v41, v169
	s_waitcnt lgkmcnt(0)
	v_mfma_f32_32x32x16_bf16 v[16:31], v[174:177], v[170:173], v[16:31]
	ds_read2_b64 v[174:177], v182 offset0:72 offset1:74
	v_sub_f32_e32 v42, v42, v169
	v_sub_f32_e32 v43, v43, v169
	v_sub_f32_e32 v44, v44, v169
	v_sub_f32_e32 v45, v45, v169
	v_sub_f32_e32 v46, v46, v169
	v_sub_f32_e32 v47, v47, v169
	s_waitcnt lgkmcnt(0)
	v_mfma_f32_32x32x16_bf16 v[0:15], v[174:177], v[170:173], v[0:15]
	ds_read2_b64 v[174:177], v183 offset0:12 offset1:14
	v_exp_f32_e32 v40, v40
	v_exp_f32_e32 v41, v41
	v_exp_f32_e32 v42, v42
	v_exp_f32_e32 v43, v43
	v_exp_f32_e32 v44, v44
	v_exp_f32_e32 v45, v45
	v_exp_f32_e32 v46, v46
	v_exp_f32_e32 v47, v47
	v_cvt_pk_bf16_f32 v170, v40, v41
	v_cvt_pk_bf16_f32 v171, v42, v43
	v_cvt_pk_bf16_f32 v172, v44, v45
	v_cvt_pk_bf16_f32 v173, v46, v47
	s_waitcnt lgkmcnt(0)
	s_nop 0
	v_mfma_f32_32x32x16_bf16 v[16:31], v[174:177], v[170:173], v[16:31]
	ds_read2_b64 v[174:177], v182 offset0:76 offset1:78
	s_waitcnt lgkmcnt(0)
	v_mfma_f32_32x32x16_bf16 v[0:15], v[174:177], v[170:173], v[0:15]
	s_cbranch_vccnz .LBB0_1194
	s_xor_b32 s0, s18, 1
	s_mul_i32 s1, s0, 0x3400
	s_add_i32 s1, s1, 0
	v_add3_u32 v170, s1, v156, v157
	s_waitcnt vmcnt(4)
	ds_write_b128 v170, v[88:91]
	v_add3_u32 v170, s1, v158, v159
	s_waitcnt vmcnt(3)
	ds_write_b128 v170, v[92:95]
	v_add3_u32 v170, s1, v160, v161
	s_mulk_i32 s0, 0x2400
	s_waitcnt vmcnt(2)
	ds_write_b128 v170, v[98:101]
	v_add_u32_e32 v170, s0, v162
	v_lshl_add_u32 v171, v154, 1, v170
	v_lshl_add_u32 v170, v155, 1, v170
	s_waitcnt vmcnt(1)
	ds_write_b16 v171, v102 offset:26624
	ds_write_b16_d16_hi v171, v102 offset:26768
	ds_write_b16 v171, v103 offset:26912
	ds_write_b16_d16_hi v171, v103 offset:27056
	ds_write_b16 v171, v104 offset:27200
	ds_write_b16_d16_hi v171, v104 offset:27344
	ds_write_b16 v171, v105 offset:27488
	ds_write_b16_d16_hi v171, v105 offset:27632
	s_waitcnt vmcnt(0)
	ds_write_b16 v170, v106 offset:26624
	ds_write_b16_d16_hi v170, v106 offset:26768
	ds_write_b16 v170, v107 offset:26912
	ds_write_b16_d16_hi v170, v107 offset:27056
	ds_write_b16 v170, v108 offset:27200
	ds_write_b16_d16_hi v170, v108 offset:27344
	ds_write_b16 v170, v109 offset:27488
	ds_write_b16_d16_hi v170, v109 offset:27632

; DI float silu_f(float x) { return x * __builtin_amdgcn_rcpf(1.f + __expf(-x)); }
; DI void scan_post(const P& p, int layer, int vb, int nvb) {
;     ...
;   for (int t = vb * 4 + wave; t < nrows; t += nvb * 4) {
;     float a[8], bb[8], gt[8];
;     unpack8(*(const uint4*)(o0 + (size_t)t * 512 + lane * 8), a);
;     unpack8(*(const uint4*)(o1 + (size_t)t * 512 + lane * 8), bb);
;     unpack8(*(const uint4*)(z + (size_t)t * ldz + goff + lane * 8), gt);
;     float ss = 0.f;
; #pragma unroll
;     for (int j = 0; j < 8; ++j) { a[j] += bb[j]; ss += a[j] * a[j]; }
;     ss += __shfl_xor(ss, 1); ss += __shfl_xor(ss, 2); ss += __shfl_xor(ss, 4);
;     float rms;
;     if (layer == 0) rms = rsqrtf(ss * (1.f / 64.f) + EPS);
;     else { ss += __shfl_xor(ss, 8); rms = rsqrtf(ss * (1.f / 128.f) + EPS); }
; #pragma unroll
;     for (int j = 0; j < 8; ++j) a[j] = a[j] * rms * on[j] * silu_f(gt[j]);
;     *(uint4*)(o0 + (size_t)t * 512 + lane * 8) = pack8(a);
.LBB0_1236:
	v_lshl_add_u64 v[22:23], v[10:11], 0, v[8:9]
	v_add_co_u32_e32 v24, vcc, 0xf172000, v22
	v_add_u32_e32 v14, s16, v14
	s_nop 0
	v_addc_co_u32_e32 v25, vcc, 0, v23, vcc
	global_load_dwordx4 v[18:21], v[24:25], off
	v_add_co_u32_e32 v232, vcc, s15, v22
	s_nop 1
	v_addc_co_u32_e32 v233, vcc, 0, v23, vcc
	global_load_dwordx4 v[224:227], v[232:233], off
	v_lshl_add_u64 v[232:233], v[12:13], 0, v[8:9]
	global_load_dwordx4 v[228:231], v[232:233], off offset:-8
	v_lshl_add_u64 v[10:11], v[10:11], 0, s[18:19]
	s_waitcnt vmcnt(2)
	v_lshlrev_b32_e32 v26, 16, v18
	v_and_b32_e32 v27, 0xffff0000, v18
	v_lshlrev_b32_e32 v28, 16, v19
	v_and_b32_e32 v29, 0xffff0000, v19
	v_lshlrev_b32_e32 v30, 16, v20
	v_and_b32_e32 v31, 0xffff0000, v20
	v_lshlrev_b32_e32 v32, 16, v21
	v_and_b32_e32 v33, 0xffff0000, v21
	s_waitcnt vmcnt(1)
	v_lshlrev_b32_e32 v22, 16, v224
	v_and_b32_e32 v23, 0xffff0000, v224
	v_lshlrev_b32_e32 v34, 16, v225
	v_and_b32_e32 v35, 0xffff0000, v225
	v_lshlrev_b32_e32 v36, 16, v226
	v_and_b32_e32 v37, 0xffff0000, v226
	v_lshlrev_b32_e32 v38, 16, v227
	v_and_b32_e32 v39, 0xffff0000, v227
	v_pk_add_f32 v[22:23], v[26:27], v[22:23]
	v_pk_add_f32 v[28:29], v[28:29], v[34:35]
	v_pk_mul_f32 v[26:27], v[22:23], v[22:23]
	v_pk_mul_f32 v[34:35], v[28:29], v[28:29]
	v_add_f32_e32 v26, v26, v27
	v_pk_add_f32 v[30:31], v[30:31], v[36:37]
	v_add_f32_e32 v26, v26, v34
	v_pk_mul_f32 v[36:37], v[30:31], v[30:31]
	v_add_f32_e32 v26, v35, v26
	v_pk_add_f32 v[32:33], v[32:33], v[38:39]
	v_add_f32_e32 v26, v36, v26
	v_pk_mul_f32 v[38:39], v[32:33], v[32:33]
	v_add_f32_e32 v26, v37, v26
	v_add_f32_e32 v26, v38, v26
	v_add_f32_e32 v26, v39, v26
	v_lshl_add_u64 v[12:13], v[12:13], 0, s[38:39]
	s_nop 1
	v_add_f32_dpp v26, v26, v26 quad_perm:[1,0,3,2] row_mask:0xf bank_mask:0xf
	s_nop 1
	v_add_f32_dpp v26, v26, v26 quad_perm:[2,3,0,1] row_mask:0xf bank_mask:0xf
	s_nop 1
	v_add_f32_dpp v26, v26, v26 row_half_mirror row_mask:0xf bank_mask:0xf
	v_fmamk_f32 v26, v26, 0x3c800000, v119
	v_cmp_gt_f32_e32 vcc, s9, v26
	v_mul_f32_e32 v27, 0x4b800000, v26
	s_waitcnt vmcnt(0)
	v_lshlrev_b32_e32 v42, 16, v230
	v_and_b32_e32 v43, 0xffff0000, v230
	v_mul_f32_e32 v44, 0xbfb8aa3b, v42
	v_mul_f32_e32 v45, 0xbfb8aa3b, v43
	v_exp_f32_e32 v44, v44
	v_exp_f32_e32 v45, v45
	v_lshlrev_b32_e32 v40, 16, v228
	v_and_b32_e32 v41, 0xffff0000, v228
	v_add_f32_e32 v44, 1.0, v44
	v_add_f32_e32 v45, 1.0, v45
	v_rcp_f32_e32 v44, v44
	v_rcp_f32_e32 v45, v45
	v_lshlrev_b32_e32 v18, 16, v229
	v_and_b32_e32 v19, 0xffff0000, v229
	v_cndmask_b32_e32 v26, v26, v27, vcc
	v_pk_mul_f32 v[42:43], v[44:45], v[42:43]
	v_mul_f32_e32 v44, 0xbfb8aa3b, v18
	v_mul_f32_e32 v45, 0xbfb8aa3b, v19
	v_exp_f32_e32 v44, v44
	v_exp_f32_e32 v45, v45
	v_rsq_f32_e32 v26, v26
	v_lshlrev_b32_e32 v20, 16, v231
	v_add_f32_e32 v44, 1.0, v44
	v_add_f32_e32 v45, 1.0, v45
	v_rcp_f32_e32 v44, v44
	v_rcp_f32_e32 v45, v45
	v_mul_f32_e32 v27, 0x45800000, v26
	v_cndmask_b32_e32 v26, v26, v27, vcc
	v_pk_mul_f32 v[28:29], v[28:29], v[26:27] op_sel_hi:[1,0]
	v_pk_mul_f32 v[18:19], v[44:45], v[18:19]
	v_pk_mul_f32 v[28:29], v[6:7], v[28:29]
	v_and_b32_e32 v21, 0xffff0000, v231
	v_pk_mul_f32 v[28:29], v[18:19], v[28:29]
	v_pk_mul_f32 v[18:19], v[30:31], v[26:27] op_sel_hi:[1,0]
	v_mul_f32_e32 v44, 0xbfb8aa3b, v40
	v_pk_mul_f32 v[18:19], v[0:1], v[18:19]
	v_mul_f32_e32 v45, 0xbfb8aa3b, v41
	v_pk_mul_f32 v[30:31], v[42:43], v[18:19]
	v_mul_f32_e32 v18, 0xbfb8aa3b, v20
	v_mul_f32_e32 v19, 0xbfb8aa3b, v21
	v_exp_f32_e32 v44, v44
	v_exp_f32_e32 v45, v45
	v_exp_f32_e32 v18, v18
	v_exp_f32_e32 v19, v19
	v_add_f32_e32 v44, 1.0, v44
	v_add_f32_e32 v45, 1.0, v45
	v_add_f32_e32 v18, 1.0, v18
	v_add_f32_e32 v19, 1.0, v19
	v_rcp_f32_e32 v44, v44
	v_rcp_f32_e32 v45, v45
	v_rcp_f32_e32 v18, v18
	v_rcp_f32_e32 v19, v19
	v_pk_mul_f32 v[22:23], v[22:23], v[26:27] op_sel_hi:[1,0]
	v_pk_mul_f32 v[26:27], v[32:33], v[26:27] op_sel_hi:[1,0]
	v_pk_mul_f32 v[40:41], v[44:45], v[40:41]
	v_pk_mul_f32 v[22:23], v[4:5], v[22:23]
	v_pk_mul_f32 v[26:27], v[2:3], v[26:27]
	v_pk_mul_f32 v[18:19], v[18:19], v[20:21]
	v_pk_mul_f32 v[22:23], v[40:41], v[22:23]
	v_pk_mul_f32 v[26:27], v[18:19], v[26:27]
	v_cmp_lt_i32_e32 vcc, s48, v14
	v_cvt_pk_bf16_f32 v18, v22, v23
	v_cvt_pk_bf16_f32 v19, v28, v29
	v_cvt_pk_bf16_f32 v20, v30, v31
	v_cvt_pk_bf16_f32 v21, v26, v27
	s_or_b64 s[4:5], vcc, s[4:5]
	global_store_dwordx4 v[24:25], v[18:21], off
	s_andn2_b64 exec, exec, s[4:5]
	s_cbranch_execnz .LBB0_1236
